# P5/P6 quarter units remapped on the 256-WG grid: tile = c mod 64, quarter = c / 64, so a leftover tile's four quarters (and a column panel's eight tiles) share one XCD's L2
# speedup vs baseline: 1.0034x; 1.0008x over previous
.LBB0_1119:
	s_cmp_lt_i32 s78, 6
	s_cselect_b64 s[0:1], -1, 0
	s_and_b64 s[6:7], s[0:1], s[2:3]
	s_andn2_b64 vcc, exec, s[6:7]
	s_cbranch_vccnz .LBB0_1220
	s_abs_i32 s0, s92
	v_cvt_f32_u32_e32 v0, s0
	s_sub_i32 s3, 0, s0
	s_ashr_i32 s2, s92, 31
	s_mov_b32 s1, 0
	v_rcp_iflag_f32_e32 v0, v0
	v_readfirstlane_b32 s18, v243
	v_mul_f32_e32 v0, 0x4f7ffffe, v0
	v_cvt_u32_f32_e32 v0, v0
	s_nop 0
	v_readfirstlane_b32 s4, v0
	s_mul_i32 s3, s3, s4
	s_mul_hi_u32 s3, s4, s3
	s_add_i32 s4, s4, s3
	s_mul_hi_u32 s3, s4, 0x140
	s_mul_i32 s4, s3, s0
	s_sub_i32 s4, 0x140, s4
	s_add_i32 s5, s3, 1
	s_sub_i32 s8, s4, s0
	s_cmp_ge_u32 s4, s0
	s_cselect_b32 s3, s5, s3
	s_cselect_b32 s4, s8, s4
	s_add_i32 s5, s3, 1
	s_cmp_ge_u32 s4, s0
	s_cselect_b32 s0, s5, s3
	s_xor_b32 s0, s0, s2
	s_sub_i32 s30, s0, s2
	s_mul_i32 s0, s30, s92
	s_sub_i32 s13, 0x140, s0
	s_cmp_gt_i32 s30, 0
	s_cselect_b64 s[4:5], -1, 0
	s_cmpk_lt_i32 s0, 0x140
	s_cselect_b64 s[2:3], -1, 0
	s_lshl_b32 s0, s13, 2
	s_cmp_le_i32 s0, s92
	s_cselect_b64 s[8:9], -1, 0
	s_and_b64 s[8:9], s[2:3], s[8:9]
	s_and_b64 s[2:3], s[8:9], exec
	s_cselect_b32 s12, 4, 1
	v_cvt_f32_ubyte0_e32 v0, s12
	v_rcp_iflag_f32_e32 v0, v0
	s_cmp_eq_u32 s30, 0
	s_cselect_b64 s[2:3], -1, 0
	s_and_b64 s[10:11], s[8:9], exec
	s_cselect_b32 s0, 2, 0
	s_lshl_b32 s10, s13, s0
	v_mul_f32_e32 v0, 0x4f7ffffe, v0
	s_cmp_lt_i32 s96, s10
	v_cvt_u32_f32_e32 v0, v0
	s_cselect_b64 s[10:11], -1, 0
	s_and_b64 s[2:3], s[2:3], s[10:11]
	s_or_b64 s[14:15], s[4:5], s[2:3]
	s_andn2_b64 vcc, exec, s[14:15]
	v_readfirstlane_b32 s13, v0
	s_cbranch_vccnz .LBB0_1220
	s_sub_i32 s16, 0, s12
	s_mul_i32 s16, s16, s13
	s_mul_hi_u32 s16, s13, s16
	s_ashr_i32 s14, s96, 31
	s_abs_i32 s15, s96
	s_add_i32 s13, s13, s16
	s_add_u32 s31, s76, 0x14800000
	s_mul_hi_u32 s13, s15, s13
	s_addc_u32 s33, s77, 0
	s_add_u32 s42, s76, 0x2400000
	s_mul_i32 s16, s13, s12
	s_addc_u32 s43, s77, 0
	s_lshr_b32 s17, s18, 6
	s_sub_i32 s15, s15, s16
	s_lshr_b32 s19, s18, 8
	s_lshl_b32 s20, s17, 10
	s_add_i32 s16, s13, 1
	s_sub_i32 s21, s15, s12
	s_cmp_ge_u32 s15, s12
	s_cselect_b32 s13, s16, s13
	s_cselect_b32 s15, s21, s15
	s_add_i32 s16, s13, 1
	s_cmp_ge_u32 s15, s12
	s_cselect_b32 s12, s16, s13
	s_xor_b32 s12, s12, s14
	s_sub_i32 s44, s12, s14
	s_cmpk_lg_i32 s92, 0x100
	s_cbranch_scc1 .Lrm5a
	s_and_b64 vcc, exec, s[8:9]
	s_cbranch_vccz .Lrm5a
	s_and_b32 s44, s96, 63
.Lrm5a:
	s_min_i32 s12, s30, 0
	s_and_b64 s[4:5], s[4:5], exec
	s_cselect_b32 s4, s96, s44
	s_mul_i32 s12, s12, s92
	s_add_i32 s4, s4, s12
	s_min_i32 s4, s4, 0x13f
	s_ashr_i32 s5, s4, 31
	s_lshr_b32 s5, s5, 29
	s_add_i32 s5, s4, s5
	s_ashr_i32 s12, s5, 3
	s_and_b32 s5, s5, -8
	s_sub_i32 s4, s4, s5
	s_cmp_lt_i32 s4, 0
	s_cselect_b32 s5, 41, 40
	s_mul_i32 s4, s4, s5
	s_add_i32 s4, s4, s12
	s_mul_hi_i32 s5, s4, 0x2aaaaaab
	s_lshr_b32 s12, s5, 31
	s_ashr_i32 s5, s5, 2
	s_add_i32 s5, s5, s12
	s_mul_i32 s12, s5, 3
	s_sub_i32 s13, 40, s12
	s_min_u32 s13, s13, 3
	s_mul_i32 s5, s5, 24
	s_sub_i32 s14, s4, s5
	v_cvt_f32_ubyte0_e32 v1, s13
	v_cvt_f32_i32_e32 v0, s14
	v_rcp_iflag_f32_e32 v2, v1
	s_ashr_i32 s4, s14, 30
	s_lshl_b32 s0, s44, s0
	s_or_b32 s15, s4, 1
	v_mul_f32_e32 v2, v0, v2
	v_trunc_f32_e32 v2, v2
	v_fma_f32 v0, -v2, v1, v0
	v_cvt_i32_f32_e32 v2, v2
	v_cmp_ge_f32_e64 s[4:5], |v0|, v1
	s_and_b64 s[4:5], s[4:5], exec
	s_cselect_b32 s4, s15, 0
	v_readfirstlane_b32 s5, v2
	s_add_i32 s16, s5, s4
	s_mul_i32 s4, s16, s13
	s_sub_i32 s4, s14, s4
	s_sext_i32_i8 s4, s4
	s_sub_i32 s45, s96, s0
	s_cmpk_lg_i32 s92, 0x100
	s_cbranch_scc1 .Lrm5b
	s_and_b64 vcc, exec, s[8:9]
	s_cbranch_vccz .Lrm5b
	s_lshr_b32 s45, s96, 6
.Lrm5b:
	v_lshlrev_b32_e32 v0, 4, v243
	s_add_i32 s4, s12, s4
	s_and_b64 s[2:3], s[8:9], s[2:3]
	s_add_i32 s45, s45, 1
	v_add_u32_e32 v1, 0x2000, v0
	v_and_b32_e32 v3, 32, v243
	s_and_b64 s[2:3], s[2:3], exec
	v_lshrrev_b32_e32 v2, 7, v1
	v_bfe_u32 v12, v243, 2, 4
	s_movk_i32 s0, 0xf0
	v_bitop3_b32 v10, v0, v3, 48 bitop3:0x6c
	v_and_b32_e32 v11, 64, v243
	s_cselect_b32 s76, s45, 0
	v_and_or_b32 v2, v2, s0, v12
	v_or_b32_e32 v0, v10, v11
	v_lshl_or_b32 v196, v2, 12, v0
	v_lshrrev_b32_e32 v2, 3, v243
	s_movk_i32 s0, 0x70
	s_cmp_gt_i32 s76, 0
	v_and_or_b32 v2, v2, s0, v12
	s_cselect_b64 s[12:13], -1, 0
	s_lshl_b32 s0, s76, 6
	s_sub_i32 s0, s0, 64
	s_and_b32 s0, s0, 0xffffff80
	s_ashr_i32 s5, s4, 31
	s_lshl_b64 s[0:1], s[0:1], 12
	s_lshl_b64 s[2:3], s[4:5], 20
	s_add_u32 s5, s31, s2
	s_addc_u32 s14, s33, s3
	s_not_b32 s2, s76
	s_lshl_b32 s2, s2, 19
	s_and_b32 s15, s2, 0x80000
	s_and_b64 s[2:3], s[12:13], exec
	s_cselect_b32 s15, s15, 0
	s_bfe_i64 s[2:3], s[16:17], 0x80000
	s_lshl_b64 s[2:3], s[2:3], 20
	s_add_u32 s2, s42, s2
	s_addc_u32 s3, s43, s3
	s_add_u32 s2, s2, s15
	s_addc_u32 s3, s3, 0
	s_add_i32 s48, s20, 0
	s_add_i32 s49, s48, 0x10000
	s_add_i32 s50, s48, 0x12000
	s_and_b64 s[12:13], s[12:13], exec
	v_lshl_or_b32 v198, v2, 12, v0
	s_mov_b32 m0, s49
	s_cselect_b32 s12, s1, 0
	s_cselect_b32 s13, s0, 0
	s_add_u32 s0, s2, 0x80000
	global_load_lds_dwordx4 v198, s[2:3]
	s_mov_b32 m0, s50
	s_addc_u32 s1, s3, 0
	s_add_i32 s51, s48, 0x14000
	s_waitcnt lgkmcnt(0)
	s_add_i32 s60, s48, 0x16000
	global_load_lds_dwordx4 v196, s[2:3]
	s_mov_b32 m0, s51
	s_add_u32 s34, s5, s13
	global_load_lds_dwordx4 v198, s[0:1]
	s_mov_b32 m0, s60
	s_addc_u32 s35, s14, s12
	s_add_i32 s61, s48, 0x2000
	global_load_lds_dwordx4 v196, s[0:1]
	s_mov_b32 m0, s48
	s_add_u32 s0, s34, 0x80000
	global_load_lds_dwordx4 v198, s[34:35]
	s_mov_b32 m0, s61
	s_addc_u32 s1, s35, 0
	s_add_i32 s62, s48, 0x4000
	global_load_lds_dwordx4 v196, s[34:35]
	s_mov_b32 m0, s62
	s_add_i32 s63, s48, 0x6000
	global_load_lds_dwordx4 v198, s[0:1]
	s_mov_b32 m0, s63
	v_mov_b32_e32 v0, 0
	global_load_lds_dwordx4 v196, s[0:1]
	v_mov_b32_e32 v199, v0
	v_mov_b32_e32 v197, v0
	s_cmp_eq_u32 s19, 1
	v_lshl_add_u64 v[8:9], s[2:3], 0, v[198:199]
	v_lshl_add_u64 v[6:7], s[2:3], 0, v[196:197]
	v_lshl_add_u64 v[2:3], s[34:35], 0, v[198:199]
	s_cselect_b64 s[12:13], -1, 0
	s_cmp_lg_u32 s19, 1
	v_lshl_add_u64 v[4:5], s[34:35], 0, v[196:197]
	s_cbranch_scc1 .LBB0_1123
	s_barrier

.LBB0_1270:
	s_cmp_lt_i32 s78, 7
	s_cselect_b64 s[2:3], -1, 0
	s_and_b64 s[6:7], s[2:3], s[0:1]
	s_andn2_b64 vcc, exec, s[6:7]
	s_cbranch_vccnz .LBB0_1331
	s_abs_i32 s0, s92
	v_cvt_f32_u32_e32 v0, s0
	s_sub_i32 s2, 0, s0
	s_ashr_i32 s1, s92, 31
	v_readfirstlane_b32 s16, v243
	v_rcp_iflag_f32_e32 v0, v0
	s_nop 0
	v_mul_f32_e32 v0, 0x4f7ffffe, v0
	v_cvt_u32_f32_e32 v0, v0
	s_nop 0
	v_readfirstlane_b32 s3, v0
	s_mul_i32 s2, s2, s3
	s_mul_hi_u32 s2, s3, s2
	s_add_i32 s3, s3, s2
	s_mul_hi_u32 s2, s3, 0x140
	s_mul_i32 s3, s2, s0
	s_sub_i32 s3, 0x140, s3
	s_add_i32 s4, s2, 1
	s_sub_i32 s5, s3, s0
	s_cmp_ge_u32 s3, s0
	s_cselect_b32 s2, s4, s2
	s_cselect_b32 s3, s5, s3
	s_add_i32 s4, s2, 1
	s_cmp_ge_u32 s3, s0
	s_cselect_b32 s0, s4, s2
	s_xor_b32 s0, s0, s1
	s_sub_i32 s30, s0, s1
	s_mul_i32 s20, s30, s92
	s_sub_i32 s22, 0x140, s20
	s_cmpk_lt_i32 s20, 0x140
	s_cselect_b64 s[0:1], -1, 0
	s_lshl_b32 s21, s22, 2
	s_cmp_le_i32 s21, s92
	s_cselect_b64 s[2:3], -1, 0
	s_and_b64 s[0:1], s[0:1], s[2:3]
	s_and_b64 s[2:3], s[0:1], exec
	s_cselect_b32 s9, 4, 1
	v_cvt_f32_ubyte0_e32 v0, s9
	s_cmp_gt_i32 s30, 0
	v_rcp_iflag_f32_e32 v0, v0
	s_cselect_b64 s[4:5], -1, 0
	s_cmp_eq_u32 s30, 0
	s_cselect_b64 s[2:3], -1, 0
	s_and_b64 s[10:11], s[0:1], exec
	s_cselect_b32 s8, 2, 0
	s_lshl_b32 s10, s22, s8
	v_mul_f32_e32 v0, 0x4f7ffffe, v0
	s_cmp_lt_i32 s96, s10
	v_cvt_u32_f32_e32 v0, v0
	s_cselect_b64 s[10:11], -1, 0
	s_and_b64 s[2:3], s[2:3], s[10:11]
	s_or_b64 s[10:11], s[4:5], s[2:3]
	s_andn2_b64 vcc, exec, s[10:11]
	v_readfirstlane_b32 s10, v0
	s_cbranch_vccnz .LBB0_1331
	s_sub_i32 s11, 0, s9
	s_mul_i32 s11, s11, s10
	s_mul_hi_u32 s11, s10, s11
	s_ashr_i32 s24, s96, 31
	s_abs_i32 s25, s96
	s_add_i32 s10, s10, s11
	s_add_u32 s31, s76, 0x12000000
	s_mul_hi_u32 s10, s25, s10
	s_addc_u32 s33, s77, 0
	s_add_u32 s42, s76, 0x2c00000
	s_mul_i32 s12, s10, s9
	s_addc_u32 s43, s77, 0
	s_lshr_b32 s14, s16, 6
	s_sub_i32 s12, s25, s12
	s_lshr_b32 s17, s16, 8
	s_lshl_b32 s11, s14, 10
	s_add_i32 s13, s10, 1
	s_sub_i32 s15, s12, s9
	s_cmp_ge_u32 s12, s9
	s_cselect_b32 s10, s13, s10
	s_cselect_b32 s12, s15, s12
	s_add_i32 s13, s10, 1
	s_cmp_ge_u32 s12, s9
	s_cselect_b32 s9, s13, s10
	s_xor_b32 s9, s9, s24
	s_sub_i32 s9, s9, s24
	s_cmpk_lg_i32 s92, 0x100
	s_cbranch_scc1 .Lrm6a
	s_and_b64 vcc, exec, s[0:1]
	s_cbranch_vccz .Lrm6a
	s_and_b32 s9, s96, 63
.Lrm6a:
	s_min_i32 s10, s30, 0
	s_and_b64 s[4:5], s[4:5], exec
	s_cselect_b32 s4, s96, s9
	s_mul_i32 s10, s10, s92
	s_add_i32 s4, s4, s10
	s_min_i32 s4, s4, 0x13f
	s_ashr_i32 s5, s4, 31
	s_lshr_b32 s5, s5, 29
	s_add_i32 s5, s4, s5
	s_ashr_i32 s10, s5, 3
	s_and_b32 s5, s5, -8
	s_sub_i32 s4, s4, s5
	s_cmp_lt_i32 s4, 0
	s_cselect_b32 s5, 41, 40
	s_mul_i32 s12, s4, s5
	s_lshl_b32 s4, s9, s8
	s_sub_i32 s8, s96, s4
	s_cmpk_lg_i32 s92, 0x100
	s_cbranch_scc1 .Lrm6b
	s_and_b64 vcc, exec, s[0:1]
	s_cbranch_vccz .Lrm6b
	s_lshr_b32 s8, s96, 6
.Lrm6b:
	s_and_b64 s[4:5], s[2:3], exec
	s_cselect_b32 s9, s8, 0
	s_add_i32 s12, s12, s10
	s_mul_hi_i32 s4, s12, 0x2aaaaaab
	s_lshr_b32 s5, s4, 31
	s_ashr_i32 s4, s4, 2
	s_add_i32 s4, s4, s5
	s_mul_i32 s10, s4, 3
	s_sub_i32 s5, 40, s10
	s_min_u32 s13, s5, 3
	s_mul_i32 s4, s4, 24
	s_sub_i32 s12, s12, s4
	v_cvt_f32_ubyte0_e32 v1, s13
	v_cvt_f32_i32_e32 v0, s12
	v_rcp_iflag_f32_e32 v2, v1
	s_ashr_i32 s4, s12, 30
	s_or_b32 s15, s4, 1
	v_and_b32_e32 v3, 32, v243
	v_mul_f32_e32 v2, v0, v2
	v_trunc_f32_e32 v2, v2
	v_fma_f32 v0, -v2, v1, v0
	v_cvt_i32_f32_e32 v2, v2
	v_cmp_ge_f32_e64 s[4:5], |v0|, v1
	s_and_b64 s[4:5], s[4:5], exec
	s_cselect_b32 s4, s15, 0
	v_readfirstlane_b32 s5, v2
	s_add_i32 s26, s5, s4
	s_mul_i32 s4, s26, s13
	s_sub_i32 s4, s12, s4
	s_sext_i32_i8 s4, s4
	s_add_i32 s78, s10, s4
	s_add_i32 s8, s8, 1
	s_and_b64 s[2:3], s[2:3], exec
	v_lshlrev_b32_e32 v0, 4, v243
	s_cselect_b32 s4, s8, 0
	s_and_b64 s[2:3], s[0:1], exec
	v_add_u32_e32 v1, 0x2000, v0
	s_cselect_b32 s79, s4, s9
	v_lshrrev_b32_e32 v2, 7, v1
	v_bfe_u32 v12, v243, 2, 4
	s_movk_i32 s2, 0xf0
	v_bitop3_b32 v10, v0, v3, 48 bitop3:0x6c
	v_and_b32_e32 v11, 64, v243
	v_and_or_b32 v2, v2, s2, v12
	v_or_b32_e32 v0, v10, v11
	s_lshl_b32 s4, s79, 6
	s_not_b32 s8, s79
	v_lshl_or_b32 v228, v2, 12, v0
	v_lshrrev_b32_e32 v2, 3, v243
	s_movk_i32 s2, 0x70
	s_lshl_b32 s3, s78, 8
	s_sub_i32 s4, s4, 64
	s_lshl_b32 s8, s8, 19
	v_and_or_b32 v2, v2, s2, v12
	s_lshl_b32 s2, s9, 5
	s_and_b32 s4, s4, 0xffffff80
	s_ashr_i32 s5, s3, 31
	s_and_b32 s8, s8, 0x80000
	s_cmp_gt_i32 s79, 0
	s_cselect_b32 s4, s4, 0
	s_cselect_b32 s8, s8, 0
	s_add_u32 s4, s3, s4
	s_addc_u32 s5, s5, 0
	s_ashr_i32 s3, s2, 31
	s_lshl_b64 s[4:5], s[4:5], 12
	s_lshl_b64 s[2:3], s[2:3], 7
	s_and_b64 s[0:1], s[0:1], exec
	s_cselect_b32 s3, 0, s3
	s_cselect_b32 s2, 0, s2
	s_add_u32 s9, s31, s4
	s_addc_u32 s10, s33, s5
	s_bfe_i64 s[0:1], s[26:27], 0x80000
	s_lshl_b64 s[0:1], s[0:1], 20
	s_add_u32 s4, s42, s2
	s_addc_u32 s5, s43, s3
	s_add_u32 s0, s4, s0
	s_addc_u32 s1, s5, s1
	s_add_u32 s4, s0, s8
	s_addc_u32 s5, s1, 0
	s_add_i32 s44, s11, 0
	s_add_i32 s45, s44, 0x10000
	s_add_i32 s48, s44, 0x12000
	v_lshl_or_b32 v230, v2, 12, v0
	s_mov_b32 m0, s45
	s_add_u32 s0, s4, 0x80000
	global_load_lds_dwordx4 v230, s[4:5]
	s_mov_b32 m0, s48
	s_addc_u32 s1, s5, 0
	s_add_i32 s49, s44, 0x14000
	s_add_i32 s50, s44, 0x16000
	global_load_lds_dwordx4 v228, s[4:5]
	s_mov_b32 m0, s49
	s_add_u32 s38, s9, s2
	global_load_lds_dwordx4 v230, s[0:1]
	s_mov_b32 m0, s50
	s_addc_u32 s39, s10, s3
	s_add_i32 s51, s44, 0x2000
	global_load_lds_dwordx4 v228, s[0:1]
	s_mov_b32 m0, s44
	s_add_u32 s0, s38, 0x80000
	global_load_lds_dwordx4 v230, s[38:39]
	s_mov_b32 m0, s51
	s_addc_u32 s1, s39, 0
	s_add_i32 s56, s44, 0x4000
	global_load_lds_dwordx4 v228, s[38:39]
	s_mov_b32 m0, s56
	s_add_i32 s57, s44, 0x6000
	global_load_lds_dwordx4 v230, s[0:1]
	s_mov_b32 m0, s57
	v_mov_b32_e32 v0, 0
	global_load_lds_dwordx4 v228, s[0:1]
	v_mov_b32_e32 v231, v0
	v_mov_b32_e32 v229, v0
	s_cmp_eq_u32 s17, 1
	s_movk_i32 s58, 0x2000
	v_lshl_add_u64 v[8:9], s[4:5], 0, v[230:231]
	v_lshl_add_u64 v[6:7], s[4:5], 0, v[228:229]
	v_lshl_add_u64 v[2:3], s[38:39], 0, v[230:231]
	s_cselect_b64 s[8:9], -1, 0
	s_cmp_lg_u32 s17, 1
	v_lshl_add_u64 v[4:5], s[38:39], 0, v[228:229]
	s_cbranch_scc1 .LBB0_1274
	s_barrier
